# speedup vs baseline: 1.0116x; 1.0097x over previous
.LBB0_205:
	v_writelane_b32 v253, s50, 6
	s_nop 1
	v_writelane_b32 v253, s51, 7
	s_or_b64 exec, exec, s[36:37]
	s_load_dwordx2 s[8:9], s[0:1], 0xc0
	s_load_dwordx4 s[36:39], s[0:1], 0xb8
	s_load_dwordx2 s[16:17], s[0:1], 0x0
	v_mbcnt_lo_u32_b32 v0, -1, 0
	v_mov_b32_e32 v1, 0
	s_waitcnt lgkmcnt(0)
	s_add_u32 s94, s8, 0xba00000
	s_addc_u32 s70, s9, 0
	s_add_u32 s48, s8, 0xfa00000
	s_addc_u32 s49, s9, 0
	s_add_u32 s71, s8, 0x1fa00000
	s_addc_u32 s72, s9, 0
	s_add_u32 s50, s8, 0x2be00000
	s_addc_u32 s51, s9, 0
	s_add_u32 s74, s38, 0x23a00000
	s_addc_u32 s75, s39, 0
	s_add_u32 s2, s38, 0xba00000
	s_addc_u32 s3, s39, 0
	v_writelane_b32 v253, s2, 8
	v_mov_b32_e32 v208, 1
	v_mov_b32_e32 v210, 0x358637bd
	v_writelane_b32 v253, s3, 9
	s_add_u32 s2, s38, 0x27e00000
	s_addc_u32 s3, s39, 0
	v_writelane_b32 v253, s2, 10
	v_mov_b32_e32 v211, 0x260
	v_mov_b32_e32 v209, 0x3727c5ac
	v_writelane_b32 v253, s3, 11
	s_add_u32 s2, s38, 0x40000
	s_addc_u32 s3, s39, 0
	v_writelane_b32 v253, s2, 12
	v_mov_b64_e32 v[250:251], 0x800
	v_mov_b64_e32 v[186:187], 0x7ff
	v_writelane_b32 v253, s3, 13
	s_add_u32 s2, s38, 0x1fa00000
	v_writelane_b32 v253, s2, 14
	s_addc_u32 s2, s39, 0
	v_writelane_b32 v253, s2, 15
	s_add_u32 s2, s38, 0x27a00000
	v_writelane_b32 v253, s2, 16
	s_addc_u32 s2, s39, 0
	v_writelane_b32 v253, s2, 17
	s_add_u32 s2, s38, 0x29e00000
	s_addc_u32 s3, s39, 0
	s_add_u32 s73, s8, 0x2a00000
	v_writelane_b32 v253, s2, 18
	s_addc_u32 s10, s9, 0
	v_mbcnt_hi_u32_b32 v215, -1, v0
	v_writelane_b32 v253, s3, 19
	s_add_u32 s2, s8, 0x10000
	s_addc_u32 s3, s9, 0
	v_writelane_b32 v253, s2, 20
	s_cmpk_lt_i32 s95, 0x400
	v_mov_b32_e32 v216, 0x41b17218
	v_writelane_b32 v253, s3, 21
	s_cselect_b64 s[2:3], -1, 0
	v_writelane_b32 v253, s2, 22
	s_ashr_i32 s97, s95, 31
	s_ashr_i32 s96, s54, 31
	v_writelane_b32 v253, s3, 23
	s_lshr_b32 s2, s97, 29
	s_add_i32 s3, s95, s2
	s_ashr_i32 s2, s3, 3
	s_and_b32 s3, s3, -8
	s_sub_i32 s3, s95, s3
	s_lshl_b32 s4, s3, 7
	s_add_u32 s11, s8, 0x200000
	s_addc_u32 s12, s9, 0
	s_add_u32 s6, s8, 0x100000
	s_addc_u32 s7, s9, 0
	v_writelane_b32 v253, s6, 24
	s_movk_i32 s33, 0x2000
	s_movk_i32 s40, 0x4000
	v_writelane_b32 v253, s7, 25
	s_add_u32 s6, s8, 0x180000
	s_addc_u32 s7, s9, 0
	v_writelane_b32 v253, s6, 26
	s_cmpk_lt_i32 s95, 0x800
	s_movk_i32 s41, 0x6000
	v_writelane_b32 v253, s7, 27
	s_cselect_b64 s[6:7], -1, 0
	v_writelane_b32 v253, s6, 28
	s_lshl_b32 s5, s3, 8
	s_mov_b32 s44, 0x8000
	v_writelane_b32 v253, s7, 29
	s_add_u32 s6, s8, 0x13a00000
	v_writelane_b32 v253, s6, 30
	s_addc_u32 s6, s9, 0
	s_add_u32 s76, s38, 0x1ba00000
	s_addc_u32 s77, s39, 0
	v_writelane_b32 v253, s6, 31
	s_add_u32 s6, s38, 0x30000
	v_writelane_b32 v253, s6, 32
	s_addc_u32 s6, s39, 0
	v_writelane_b32 v253, s6, 33
	s_add_u32 s6, s38, 0x80000
	s_addc_u32 s7, s39, 0
	v_writelane_b32 v253, s6, 34
	s_mov_b32 s45, 0xa000
	s_mov_b32 s42, 0xc000
	v_writelane_b32 v253, s7, 35
	s_add_u32 s6, s38, 0xfa00000
	s_addc_u32 s7, s39, 0
	v_writelane_b32 v253, s6, 36
	s_mov_b32 s63, 0x800000
	s_mov_b32 s61, 0x3f317217
	v_writelane_b32 v253, s7, 37
	s_add_u32 s6, s38, 0x11a00000
	s_addc_u32 s7, s39, 0
	v_writelane_b32 v253, s6, 38
	s_mov_b32 s64, 0x41000000
	s_mov_b32 s65, 0xf800000
	v_writelane_b32 v253, s7, 39
	s_add_u32 s6, s38, 0x13a00000
	v_writelane_b32 v253, s6, 40
	s_addc_u32 s6, s39, 0
	v_writelane_b32 v253, s6, 41
	s_add_u32 s6, s38, 0x20000
	s_addc_u32 s7, s39, 0
	s_add_u32 s86, s38, 0x15a00000
	s_addc_u32 s87, s39, 0
	s_add_u32 s88, s38, 0x17a00000
	s_addc_u32 s89, s39, 0
	s_add_u32 s90, s38, 0x19a00000
	v_writelane_b32 v253, s6, 42
	s_addc_u32 s91, s39, 0
	s_mov_b32 s43, 0
	v_writelane_b32 v253, s7, 43
	s_add_u32 s6, s38, 0x1da00000
	v_writelane_b32 v253, s6, 44
	s_addc_u32 s6, s39, 0
	v_writelane_b32 v253, s6, 45
	s_add_u32 s6, s38, 0x31000
	v_writelane_b32 v253, s6, 46
	s_addc_u32 s6, s39, 0
	v_writelane_b32 v253, s6, 47
	s_add_u32 s6, s38, 0x23a10000
	v_writelane_b32 v253, s6, 48
	s_addc_u32 s6, s39, 0
	s_add_u32 s13, s8, 0x2200000
	s_addc_u32 s14, s9, 0
	v_writelane_b32 v253, s6, 49
	s_add_u32 s6, s8, 0x4000
	s_addc_u32 s7, s9, 0
	v_writelane_b32 v253, s6, 50
	s_cmpk_lt_i32 s95, 0x200
	s_mov_b64 s[84:85], 0x400000
	v_writelane_b32 v253, s7, 51
	s_cselect_b64 s[6:7], -1, 0
	v_writelane_b32 v253, s6, 52
	s_mov_b64 s[52:53], 0x80
	s_mov_b32 s60, 0x3fb504f3
	v_writelane_b32 v253, s7, 53
	s_lshl_b32 s6, s3, 6
	s_add_u32 s7, s8, 0x3a00000
	v_writelane_b32 v253, s7, 54
	s_addc_u32 s7, s9, 0
	v_writelane_b32 v253, s7, 55
	s_add_u32 s7, s8, 0x7a00000
	v_writelane_b32 v253, s7, 56
	s_addc_u32 s7, s9, 0
	v_writelane_b32 v253, s7, 57
	v_writelane_b32 v253, s16, 58
	s_mul_i32 s7, s3, 0x81
	s_mov_b32 s62, 0x3e38aa3b
	v_writelane_b32 v253, s17, 59
	s_load_dwordx4 s[16:19], s[0:1], 0x20
	s_waitcnt lgkmcnt(0)
	s_barrier
	s_add_u32 s20, s16, 0x2000
	s_addc_u32 s21, s17, 0
	v_writelane_b32 v253, s20, 60
	s_nop 1
	v_writelane_b32 v253, s21, 61
	s_add_u32 s20, s18, 0x2000
	v_writelane_b32 v253, s16, 62
	s_addc_u32 s21, s19, 0
	s_nop 0
	v_writelane_b32 v254, s18, 0
	v_writelane_b32 v254, s19, 1
	s_add_u32 s16, s8, 0xc000
	v_writelane_b32 v253, s17, 63
	v_writelane_b32 v254, s20, 2
	s_addc_u32 s17, s9, 0
	s_add_u32 s8, s8, 0xe000
	v_writelane_b32 v254, s21, 3
	v_writelane_b32 v254, s16, 4
	s_addc_u32 s9, s9, 0
	s_cmp_lt_i32 s3, 0
	v_writelane_b32 v254, s17, 5
	v_writelane_b32 v254, s8, 6
	s_cselect_b32 s4, s7, s4
	s_mul_i32 s7, s3, 0x101
	s_mulk_i32 s3, 0x41
	v_writelane_b32 v254, s9, 7
	s_cselect_b32 s8, s7, s5
	s_cselect_b32 s3, s3, s6
	s_add_i32 s4, s4, s2
	s_ashr_i32 s5, s4, 31
	s_lshr_b32 s5, s5, 25
	s_add_i32 s5, s4, s5
	s_and_b32 s6, s5, 0xff80
	s_sub_i32 s4, s4, s6
	s_bfe_i32 s6, s4, 0x80000
	s_bfe_u32 s6, s6, 0x3000c
	s_add_i32 s6, s4, s6
	s_and_b32 s7, s6, 0xf8
	s_sub_i32 s4, s4, s7
	s_ashr_i32 s5, s5, 7
	s_bfe_i32 s6, s6, 0x80000
	s_lshl_b32 s5, s5, 3
	s_sext_i32_i16 s6, s6
	s_sext_i32_i8 s4, s4
	s_add_i32 s16, s5, s4
	s_ashr_i32 s4, s6, 3
	v_writelane_b32 v254, s4, 8
	s_lshr_b32 s4, s6, 3
	s_mov_b32 s6, s16
	s_ashr_i32 s17, s16, 31
	s_bfe_i64 s[4:5], s[4:5], 0x100000
	v_writelane_b32 v254, s6, 9
	s_lshl_b64 s[4:5], s[4:5], 20
	s_nop 0
	v_writelane_b32 v254, s7, 10
	s_lshl_b64 s[6:7], s[16:17], 20
	s_add_u32 s4, s73, s4
	s_addc_u32 s5, s10, s5
	s_add_u32 s16, s4, 0x80000
	v_writelane_b32 v254, s10, 11
	s_addc_u32 s17, s5, 0
	v_writelane_b32 v254, s16, 12
	s_add_u32 s6, s71, s6
	s_addc_u32 s7, s72, s7
	v_writelane_b32 v254, s17, 13
	s_add_u32 s16, s6, 0x80000
	v_writelane_b32 v254, s6, 14
	s_addc_u32 s17, s7, 0
	s_nop 0
	v_writelane_b32 v254, s7, 15
	v_writelane_b32 v254, s16, 16
	s_add_u32 s6, s4, 0x80080
	s_nop 0
	v_writelane_b32 v254, s17, 17
	v_writelane_b32 v254, s4, 18
	s_addc_u32 s7, s5, 0
	s_nop 0
	v_writelane_b32 v254, s5, 19
	s_add_i32 s4, s8, s2
	s_ashr_i32 s5, s4, 31
	s_lshr_b32 s5, s5, 24
	v_writelane_b32 v254, s6, 20
	s_add_i32 s5, s4, s5
	s_add_i32 s2, s3, s2
	v_writelane_b32 v254, s7, 21
	s_and_b32 s6, s5, 0xff00
	s_sub_i32 s4, s4, s6
	s_sext_i32_i16 s6, s4
	s_bfe_u32 s6, s6, 0x3001c
	s_ashr_i32 s3, s2, 31
	s_add_i32 s6, s4, s6
	s_lshr_b32 s3, s3, 26
	s_and_b32 s7, s6, 0xfff8
	s_add_i32 s3, s2, s3
	s_sub_i32 s4, s4, s7
	s_and_b32 s7, s3, 0xffc0
	s_sub_i32 s2, s2, s7
	s_bfe_i32 s7, s2, 0x80000
	s_bfe_u32 s7, s7, 0x3000c
	s_add_i32 s7, s2, s7
	s_ashr_i32 s5, s5, 8
	s_and_b32 s8, s7, 0xf8
	s_lshl_b32 s5, s5, 3
	s_sext_i32_i16 s4, s4
	s_sub_i32 s2, s2, s8
	s_add_i32 s16, s5, s4
	s_ashr_i32 s3, s3, 6
	s_bfe_i32 s4, s7, 0x80000
	s_lshl_b32 s3, s3, 3
	s_sext_i32_i16 s4, s4
	s_sext_i32_i8 s2, s2
	s_add_i32 s18, s3, s2
	s_cmpk_lg_i32 s54, 0x100
	s_cbranch_scc1 .Lmap2k_0
	s_lshr_b32 s18, s95, 3
	s_lshr_b32 s4, s18, 2
	s_lshl_b32 s4, s4, 3
	s_and_b32 s18, s18, 3
	s_and_b32 s19, s95, 7
	s_lshl_b32 s19, s19, 3
	s_add_i32 s18, s18, s19
.Lmap2k_0:
	s_ashr_i32 s2, s4, 3
	s_sext_i32_i16 s6, s6
	v_writelane_b32 v254, s2, 22
	s_lshr_b32 s2, s4, 3
	s_ashr_i32 s19, s18, 31
	s_bfe_i64 s[2:3], s[2:3], 0x100000
	s_ashr_i32 s4, s6, 3
	v_writelane_b32 v254, s4, 23
	s_lshr_b32 s4, s6, 3
	s_lshl_b64 s[6:7], s[18:19], 20
	s_lshl_b64 s[8:9], s[2:3], 20
	s_add_u32 s8, s13, s8
	v_writelane_b32 v254, s13, 24
	s_addc_u32 s9, s14, s9
	v_writelane_b32 v254, s14, 25
	s_add_u32 s14, s8, 0x80000
	s_addc_u32 s15, s9, 0
	v_writelane_b32 v254, s14, 26
	s_add_u32 s6, s71, s6
	s_addc_u32 s7, s72, s7
	v_writelane_b32 v254, s15, 27
	s_add_u32 s14, s6, 0x80000
	v_writelane_b32 v254, s6, 28
	s_addc_u32 s15, s7, 0
	s_nop 0
	v_writelane_b32 v254, s7, 29
	v_writelane_b32 v254, s14, 30
	s_add_u32 s6, s8, 0x80080
	s_nop 0
	v_writelane_b32 v254, s15, 31
	v_writelane_b32 v254, s8, 32
	s_addc_u32 s7, s9, 0
	s_bfe_i64 s[4:5], s[4:5], 0x100000
	v_writelane_b32 v254, s9, 33
	v_writelane_b32 v254, s6, 34
	s_ashr_i32 s17, s16, 31
	s_nop 0
	v_writelane_b32 v254, s7, 35
	s_lshl_b64 s[6:7], s[4:5], 20
	s_mov_b32 s4, s16
	v_writelane_b32 v254, s4, 36
	s_nop 1
	v_writelane_b32 v254, s5, 37
	s_lshl_b64 s[4:5], s[16:17], 20
	s_add_u32 s4, s94, s4
	s_addc_u32 s5, s70, s5
	s_add_u32 s8, s4, 0x80000
	v_writelane_b32 v254, s4, 38
	s_addc_u32 s9, s5, 0
	s_lshl_b64 s[2:3], s[2:3], 22
	v_writelane_b32 v254, s5, 39
	v_writelane_b32 v254, s8, 40
	s_nop 1
	v_writelane_b32 v254, s9, 41
	v_writelane_b32 v254, s2, 42
	s_nop 1
	v_writelane_b32 v254, s3, 43
	s_mov_b32 s2, s18
	v_writelane_b32 v254, s2, 44
	s_nop 1
	v_writelane_b32 v254, s3, 45
	s_lshl_b64 s[2:3], s[18:19], 22
	s_add_u32 s4, s48, s2
	s_mul_i32 s2, s55, s54
	s_mul_i32 s2, s2, s57
	s_addc_u32 s5, s49, s3
	v_writelane_b32 v253, s2, 2
	s_load_dwordx2 s[2:3], s[0:1], 0x48
	s_mov_b32 s55, 0x7f800000
	s_load_dwordx2 s[0:1], s[0:1], 0x58
	s_waitcnt lgkmcnt(0)
	v_writelane_b32 v254, s2, 46
	s_nop 1
	v_writelane_b32 v254, s3, 47
	v_writelane_b32 v254, s0, 48
	s_nop 1
	v_writelane_b32 v254, s1, 49
	s_add_u32 s0, s4, 0x200000
	v_writelane_b32 v254, s4, 50
	s_addc_u32 s1, s5, 0
	s_nop 0
	v_writelane_b32 v254, s5, 51
	v_writelane_b32 v254, s0, 52
	s_nop 1
	v_writelane_b32 v254, s1, 53
	v_writelane_b32 v254, s11, 54
	s_add_u32 s0, s11, s6
	v_writelane_b32 v254, s12, 55
	v_writelane_b32 v254, s6, 56
	s_addc_u32 s1, s12, s7
	s_add_u32 s2, s0, 0x80000
	v_writelane_b32 v254, s7, 57
	s_addc_u32 s3, s1, 0
	v_writelane_b32 v254, s2, 58
	s_nop 1
	v_writelane_b32 v254, s3, 59
	s_add_u32 s2, s0, 0x80080
	v_writelane_b32 v254, s0, 60
	s_addc_u32 s3, s1, 0
	s_lshl_b32 s78, s54, 5
	s_lshl_b32 s79, s54, 4
	v_writelane_b32 v254, s1, 61
	s_add_u32 s0, s38, 0x13a04000
	s_addc_u32 s1, s39, 0
	v_writelane_b32 v255, s0, 0
	s_ashr_i32 s69, s68, 31
	v_writelane_b32 v254, s2, 62
	v_writelane_b32 v255, s1, 1
	s_add_i32 s0, 0, 0x22000
	v_writelane_b32 v255, s0, 2
	s_add_i32 s0, 0, 0x22a00
	v_writelane_b32 v255, s0, 3
	s_add_i32 s0, 0, 0x22800
	v_writelane_b32 v255, s0, 4
	s_add_i32 s0, 0, 0x11800
	v_writelane_b32 v255, s0, 5
	s_add_i32 s0, 0, 0x4400
	v_writelane_b32 v255, s0, 6
	s_add_i32 s0, 0, 0x22c00
	v_writelane_b32 v255, s0, 7
	s_mov_b32 s0, 0
	v_writelane_b32 v255, s0, 8
	s_lshl_b64 s[0:1], s[68:69], 12
	v_writelane_b32 v255, s0, 9
	v_writelane_b32 v254, s3, 63
	s_mov_b64 s[2:3], -1
	v_writelane_b32 v255, s1, 10
	s_lshl_b64 s[0:1], s[68:69], 13
	v_writelane_b32 v255, s0, 11
	v_writelane_b32 v253, s78, 4
	s_nop 0
	v_writelane_b32 v255, s1, 12
	s_mov_b32 s0, s68
	v_writelane_b32 v255, s0, 13
	s_nop 1
	v_writelane_b32 v255, s1, 14
	v_writelane_b32 v255, s94, 15
	v_writelane_b32 v255, s70, 16
	v_writelane_b32 v255, s71, 17
	v_writelane_b32 v255, s72, 18
	v_writelane_b32 v255, s74, 19
	s_nop 1
	v_writelane_b32 v255, s75, 20
	v_writelane_b32 v255, s73, 21
	v_writelane_b32 v255, s97, 22
	v_writelane_b32 v255, s96, 23
	v_writelane_b32 v255, s79, 24
	s_branch .LBB0_209

.LBB0_845:
	s_cmpk_lg_i32 s54, 0x100
	s_cbranch_scc1 .Lmap2k_1
	s_lshr_b32 s12, s95, 3
	s_lshr_b32 s10, s12, 2
	s_and_b32 s12, s12, 3
	s_and_b32 s13, s95, 7
	s_lshl_b32 s13, s13, 3
	s_add_i32 s12, s12, s13
	s_lshl_b32 s13, s28, 2
	s_add_i32 s12, s12, s13

.LBB0_1023:
	s_cmpk_lg_i32 s54, 0x100
	s_cbranch_scc1 .Lmap2k_2
	s_lshr_b32 s14, s95, 3
	s_lshr_b32 s12, s14, 2
	s_and_b32 s14, s14, 3
	s_and_b32 s15, s95, 7
	s_lshl_b32 s15, s15, 3
	s_add_i32 s14, s14, s15
	s_lshl_b32 s15, s40, 2
	s_add_i32 s14, s14, s15

.LBB0_1045:
	s_cmpk_lg_i32 s54, 0x100
	s_cbranch_scc1 .Lmap2k_3
	s_lshr_b32 s12, s95, 3
	s_lshr_b32 s10, s12, 2
	s_and_b32 s12, s12, 3
	s_and_b32 s13, s95, 7
	s_lshl_b32 s13, s13, 3
	s_add_i32 s12, s12, s13
	s_lshl_b32 s13, s34, 2
	s_add_i32 s12, s12, s13
